# attention work queue made XCD-aware (per-XCD queues, each XCD owns one heavy (b,h) stream + half of two light ones, stealing when empty) for L2 sharing of K/V tiles
# speedup vs baseline: 1.0227x; 1.0062x over previous
.LBB0_306:
	s_or_b64 exec, exec, s[0:1]
	v_readlane_b32 s0, v252, 1
	v_mov_b32_e32 v169, 0
	v_readlane_b32 s1, v252, 2
	v_mov_b32_e32 v5, 0x8000
	s_waitcnt lgkmcnt(0)
	s_barrier
	v_add_f32_e32 v2, v0, v2
	s_nop 0
	global_load_dword v4, v169, s[0:1] sc1
	v_add_f32_e32 v1, v1, v3
	global_load_dword v5, v5, s[62:63] offset:768 sc1
	s_mov_b32 s0, 0x3fb8aa3b
	v_lshrrev_b32_e32 v7, 4, v209
	v_lshlrev_b32_e32 v10, 4, v209
	v_mul_f32_e32 v13, 0x3fb8aa3b, v2
	v_lshrrev_b32_e32 v8, 5, v209
	v_lshrrev_b32_e32 v9, 3, v209
	v_mul_f32_e32 v14, 0x3fb8aa3b, v1
	v_and_b32_e32 v15, 51, v7
	v_and_b32_e32 v17, 0xf0, v10
	v_mul_u32_u24_e32 v7, 0x1400, v7
	v_fma_f32 v20, v2, s0, -v13
	v_rndne_f32_e32 v21, v13
	v_and_b32_e32 v8, 4, v8
	v_and_b32_e32 v16, 8, v9
	v_fma_f32 v22, v1, s0, -v14
	v_rndne_f32_e32 v23, v14
	v_or_b32_e32 v170, v17, v7
	v_fmac_f32_e32 v20, 0x32a5705f, v2
	v_sub_f32_e32 v7, v13, v21
	v_or3_b32 v8, v15, v8, v16
	v_fmac_f32_e32 v22, 0x32a5705f, v1
	v_sub_f32_e32 v14, v14, v23
	v_add_f32_e32 v7, v7, v20
	v_cvt_i32_f32_e32 v13, v21
	v_mul_u32_u24_e32 v8, 0x110, v8
	v_add_f32_e32 v14, v14, v22
	v_exp_f32_e32 v7, v7
	v_cvt_i32_f32_e32 v15, v23
	v_add3_u32 v212, 0, v8, v17
	v_exp_f32_e32 v8, v14
	s_mov_b32 s1, 0xc2ce8ed0
	v_ldexp_f32 v7, v7, v13
	v_cmp_ngt_f32_e32 vcc, s1, v2
	s_mov_b32 s33, 0x42b17218
	v_ldexp_f32 v8, v8, v15
	v_cndmask_b32_e32 v7, 0, v7, vcc
	v_cmp_ngt_f32_e32 vcc, s1, v1
	v_mov_b32_e32 v3, 0x7f800000
	s_mov_b32 s38, 0xf800000
	v_cndmask_b32_e32 v8, 0, v8, vcc
	v_cmp_nlt_f32_e32 vcc, s33, v2
	s_add_u32 s4, s62, 0xc00000
	s_addc_u32 s5, s63, 0
	v_cndmask_b32_e32 v2, v3, v7, vcc
	v_cmp_nlt_f32_e32 vcc, s33, v1
	s_add_u32 s6, s62, 0xd00000
	s_addc_u32 s7, s63, 0
	v_cndmask_b32_e32 v1, v3, v8, vcc
	v_sub_f32_e32 v1, v2, v1
	v_add_f32_e32 v172, 0x3eb60549, v1
	s_add_u32 s34, s62, 0xe00000
	s_addc_u32 s35, s63, 0
	s_add_u32 s26, s62, 0x1000000
	s_addc_u32 s27, s63, 0
	v_mov_b32_e32 v6, 0x260
	s_add_u32 s24, s62, 0x1b00000
	s_addc_u32 s25, s63, 0
	s_add_u32 s36, s62, 0x1c900000
	s_addc_u32 s37, s63, 0
	v_mul_u32_u24_e32 v11, 0x110, v167
	v_lshlrev_b32_e32 v12, 4, v166
	s_add_u32 s40, s62, 0x8000
	s_addc_u32 s41, s63, 0
	v_add3_u32 v214, 0, v11, v12
	v_lshlrev_b32_e32 v0, 3, v166
	s_add_i32 s66, s64, 0xa00
	v_lshlrev_b32_e32 v168, 2, v167
	v_and_b32_e32 v18, 0x70, v10
	v_mul_u32_u24_e32 v19, 0x10080, v9
	v_mul_u32_u24_e32 v9, 0x90, v9
	v_lshl_add_u64 v[194:195], s[30:31], 0, v[168:169]
	s_movk_i32 s30, 0xff80
	s_mov_b32 s44, 0xfffb0000
	s_movk_i32 s13, 0x1400
	v_mov_b32_e32 v171, v169
	v_lshl_add_u32 v216, v129, 2, 0
	v_lshl_add_u64 v[174:175], s[56:57], 0, v[168:169]
	s_movk_i32 s67, 0x84
	v_or_b32_e32 v219, 8, v177
	s_waitcnt vmcnt(0)
	v_mul_f32_e32 v2, v4, v5
	v_mul_f32_e32 v3, 0x4f800000, v2
	v_cmp_gt_f32_e32 vcc, s38, v2
	v_or_b32_e32 v220, 16, v177
	v_or_b32_e32 v221, 24, v177
	v_cndmask_b32_e32 v2, v2, v3, vcc
	v_sqrt_f32_e32 v3, v2
	v_lshl_add_u64 v[180:181], s[54:55], 0, v[168:169]
	v_lshl_add_u64 v[184:185], s[52:53], 0, v[168:169]
	v_lshl_add_u64 v[186:187], s[48:49], 0, v[168:169]
	v_add_u32_e32 v1, -1, v3
	v_add_u32_e32 v4, 1, v3
	v_fma_f32 v5, -v1, v3, v2
	v_fma_f32 v7, -v4, v3, v2
	v_cmp_ge_f32_e64 s[0:1], 0, v5
	v_mov_b32_e32 v5, v169
	v_lshl_add_u64 v[190:191], s[46:47], 0, v[168:169]
	v_cndmask_b32_e64 v1, v3, v1, s[0:1]
	v_cmp_lt_f32_e64 s[0:1], 0, v7
	v_mov_b32_e32 v173, v172
	v_mov_b32_e32 v165, v166
	v_cndmask_b32_e64 v1, v1, v4, s[0:1]
	v_mul_f32_e32 v3, 0x37800000, v1
	v_cndmask_b32_e32 v1, v1, v3, vcc
	v_cmp_class_f32_e32 vcc, v2, v6
	s_add_i32 s0, 0, 0x12000
	v_add_u32_e32 v217, s0, v12
	v_cndmask_b32_e32 v1, v1, v2, vcc
	v_add_f32_e32 v1, v1, v1
	v_mul_f32_e32 v1, 0x3f828f5c, v1
	v_sub_f32_e32 v253, 0, v1
	v_mov_b32_e32 v254, 0x42400000
	v_cmp_lt_f32_e64 s[98:99], v1, v254
	s_nop 1
	v_cndmask_b32_e64 v253, 0, v253, s[98:99]
	s_getreg_b32 s100, hwreg(HW_REG_XCC_ID, 0, 4)
	s_and_b32 s100, s100, 7
	s_mov_b32 s101, 0
	v_fmaak_f32 v213, 2.0, v1, 0x43160000
	v_lshlrev_b32_e32 v1, 7, v167
	v_sub_u32_e32 v215, v214, v1
	s_mul_i32 s0, s78, 0x2200
	v_and_b32_e32 v1, 56, v200
	s_add_i32 s0, s0, 0
	v_mul_u32_u24_e32 v3, 0x84, v1
	v_lshlrev_b32_e32 v4, 1, v1
	v_lshlrev_b32_e32 v1, 2, v177
	v_add3_u32 v218, s0, v3, v1
	v_add_u32_e32 v1, 0, v10
	v_lshlrev_b32_e32 v2, 2, v166
	s_cmpk_lt_i32 s64, 0x1480
	v_add_u32_e32 v176, s0, v168
	s_mov_b32 s0, 0x20000
	v_add_u32_e32 v224, 0xd000, v1
	v_sub_u32_e32 v1, v167, v0
	s_cselect_b64 s[42:43], -1, 0
	v_lshl_add_u64 v[178:179], s[24:25], 0, v[4:5]
	v_lshl_add_u64 v[182:183], s[26:27], 0, v[4:5]
	v_lshl_add_u64 v[188:189], s[34:35], 0, v[4:5]
	v_lshl_add_u64 v[192:193], s[6:7], 0, v[4:5]
	v_lshl_add_u64 v[196:197], s[4:5], 0, v[4:5]
	v_cmp_gt_i32_e64 s[0:1], s0, v164
	s_lshl_b32 s68, s14, 9
	v_add3_u32 v222, 0, v9, v18
	v_add_u32_e32 v223, 0xfffffe00, v209
	v_or_b32_e32 v198, v19, v18
	v_mov_b32_e32 v199, v169
	v_add_u32_e32 v225, 0xffffff80, v1
	v_lshl_add_u32 v226, s2, 12, v200
	s_lshl_b32 s69, s14, 12
	s_mov_b64 s[52:53], 0
	s_add_i32 s70, 0, 0x12400
	v_lshlrev_b32_e32 v200, 1, v0
	s_movk_i32 s71, 0x27f
	s_mov_b32 s72, 0xc2fc0000
	s_mov_b32 s73, 0xff61b1e6
	s_mov_b32 s74, 0x40c00000
	s_mov_b32 s31, -1
	s_mov_b32 s45, -1
	v_lshlrev_b32_e32 v202, 1, v2
	v_mov_b32_e32 v227, 0x358637bd
	s_movk_i32 s75, 0x2c00
	s_mov_b64 s[46:47], 0x1000
	s_mov_b32 s76, 0x6800000
	s_mov_b32 s77, 0x1a900000
	s_mov_b32 s78, 0x6801000
	s_mov_b32 s79, 0x6802000
	s_mov_b32 s80, 0x6803000
	s_mov_b32 s81, 0x6804000
	s_mov_b64 s[48:49], 0x5000
	s_mov_b32 s82, 0x1ffff
	v_mov_b32_e32 v240, v169
	v_mov_b32_e32 v241, v169
	v_mov_b32_e32 v242, v169
	v_mov_b32_e32 v243, v169
	v_mov_b32_e32 v228, 0x42800000
	v_mov_b32_e32 v229, 0x7149f2ca
	s_branch .LBB0_309

.Lq_retry:
	s_cmp_ge_u32 s101, 8
	s_cbranch_scc1 .Lq_empty
	s_lshl_b32 s33, s100, 6
	v_mov_b32_e32 v0, s33
	v_mov_b32_e32 v1, 1
	global_atomic_add v1, v0, v1, s[40:41] sc0
	s_waitcnt vmcnt(0)
	v_readfirstlane_b32 s33, v1
	s_cmp_lt_u32 s33, 0x80
	s_cbranch_scc1 .Lq_got
	s_add_i32 s100, s100, 1
	s_and_b32 s100, s100, 7
	s_add_i32 s101, s101, 1
	s_branch .Lq_retry
.Lq_empty:
	s_movk_i32 s33, 0x400
	s_branch .Lq_write
.Lq_got:
	s_lshl_b32 s56, s100, 7
	s_or_b32 s33, s33, s56
.Lq_write:
	v_mov_b32_e32 v0, s33
	v_mov_b32_e32 v1, s70
	ds_write_b32 v1, v0

.LBB0_315:
	s_lshr_b32 s56, s64, 7
	s_and_b32 s57, s64, 0x7f
	s_lshr_b32 s55, s56, 1
	s_and_b32 s56, s56, 1
	s_cmp_lt_u32 s57, 64
	s_cbranch_scc0 .Lq_light
	s_or_b32 s54, s56, 2
	s_mov_b32 s33, s57
	s_branch .LBB0_323
.Lq_light:
	s_cmp_lt_u32 s57, 0x60
	s_cselect_b32 s54, 1, 0
	s_and_b32 s57, s57, 31
	s_lshl_b32 s57, s57, 1
	s_sub_i32 s33, 1, s56
	s_add_i32 s33, s33, s57
